# Toeplitz loops rotated: next k-step tap addresses computed while the current LDS reads are in flight
# speedup vs baseline: 1.0114x; 1.0038x over previous
.LBB0_563:
	s_ashr_i32 s0, s2, 1
	s_max_i32 s26, s0, 0
	s_and_b64 s[0:1], s[38:39], exec
	s_cselect_b32 s0, 0, s26
	s_add_i32 s1, s2, 12
	s_ashr_i32 s1, s1, 1
	s_min_i32 s1, s1, 15
	s_and_b64 s[26:27], s[38:39], exec
	s_cselect_b32 s33, s1, 15
	s_cmp_gt_i32 s0, s33
	s_cbranch_scc1 .LBB0_581
	v_lshrrev_b32_e32 v2, 1, v95
	s_lshl_b32 s1, s0, 1
	s_add_i32 s36, s0, -1
	v_or_b32_e32 v0, s1, v2
	s_lshl_b32 s0, s0, 6
	v_sub_u32_e32 v0, v0, v88
	v_sub_u32_e32 v2, v88, v2
	v_add3_u32 v3, v92, s0, v94
	s_add_i32 s0, 0, 0x9000
	v_mov_b32_e32 v4, 0
	v_add_u32_e32 v0, -12, v0
	v_subrev_u32_e32 v2, s1, v2
	v_add3_u32 v3, v3, v93, s0
	v_mov_b32_e32 v5, v4
	v_mov_b32_e32 v6, v4
	v_mov_b32_e32 v7, v4
	v_mov_b32_e32 v8, v4
	v_mov_b32_e32 v9, v4
	v_mov_b32_e32 v10, v4
	v_mov_b32_e32 v11, v4
	v_mov_b32_e32 v12, v4
	v_mov_b32_e32 v13, v4
	v_mov_b32_e32 v14, v4
	v_mov_b32_e32 v15, v4
	v_mov_b32_e32 v16, v4
	v_mov_b32_e32 v17, v4
	v_mov_b32_e32 v18, v4
	v_mov_b32_e32 v19, v4
	v_add_u32_e32 v234, 12, v0
	v_cndmask_b32_e64 v230, v234, v2, s[38:39]
	v_max_i32_e32 v242, 0, v230
	v_lshl_add_u32 v242, v242, 9, v91
	v_add_u32_e32 v235, 8, v0
	v_add_u32_e32 v239, 4, v2
	v_cndmask_b32_e64 v231, v235, v239, s[38:39]
	v_max_i32_e32 v243, 0, v231
	v_lshl_add_u32 v243, v243, 9, v91
	v_add_u32_e32 v236, 4, v0
	v_add_u32_e32 v240, 8, v2
	v_cndmask_b32_e64 v232, v236, v240, s[38:39]
	v_max_i32_e32 v244, 0, v232
	v_lshl_add_u32 v244, v244, 9, v91
	v_add_u32_e32 v241, 12, v2
	v_cndmask_b32_e64 v233, v0, v241, s[38:39]
	v_max_i32_e32 v245, 0, v233
	v_lshl_add_u32 v245, v245, 9, v91
	v_cmp_lt_i32_e64 s[98:99], -1, v230
	v_cmp_lt_i32_e64 s[100:101], -1, v231
	v_cmp_lt_i32_e64 vcc, -1, v232
	v_cndmask_b32_e64 v242, v246, v242, s[98:99]
	v_cmp_lt_i32_e64 s[98:99], -1, v233
	v_cndmask_b32_e64 v243, v246, v243, s[100:101]
	v_cndmask_b32_e64 v244, v246, v244, vcc
	s_nop 0
	v_cndmask_b32_e64 v245, v246, v245, s[98:99]
.LBB0_565:
	ds_read_b128 v[214:217], v242 offset:4096
	ds_read_b128 v[218:221], v243 offset:4096
	ds_read_b128 v[222:225], v244 offset:4096
	ds_read_b128 v[226:229], v245 offset:4096
	ds_read_b128 v[20:23], v3
	v_add_u32_e32 v0, 2, v0
	v_add_u32_e32 v2, -2, v2
	v_add_u32_e32 v3, 64, v3
	v_add_u32_e32 v234, 12, v0
	v_cndmask_b32_e64 v230, v234, v2, s[38:39]
	v_max_i32_e32 v242, 0, v230
	v_lshl_add_u32 v242, v242, 9, v91
	v_add_u32_e32 v235, 8, v0
	v_add_u32_e32 v239, 4, v2
	v_cndmask_b32_e64 v231, v235, v239, s[38:39]
	v_max_i32_e32 v243, 0, v231
	v_lshl_add_u32 v243, v243, 9, v91
	v_add_u32_e32 v236, 4, v0
	v_add_u32_e32 v240, 8, v2
	v_cndmask_b32_e64 v232, v236, v240, s[38:39]
	v_max_i32_e32 v244, 0, v232
	v_lshl_add_u32 v244, v244, 9, v91
	v_add_u32_e32 v241, 12, v2
	v_cndmask_b32_e64 v233, v0, v241, s[38:39]
	v_max_i32_e32 v245, 0, v233
	v_lshl_add_u32 v245, v245, 9, v91
	v_cmp_lt_i32_e64 s[98:99], -1, v230
	v_cmp_lt_i32_e64 s[100:101], -1, v231
	v_cmp_lt_i32_e64 vcc, -1, v232
	v_cndmask_b32_e64 v242, v246, v242, s[98:99]
	v_cmp_lt_i32_e64 s[98:99], -1, v233
	v_cndmask_b32_e64 v243, v246, v243, s[100:101]
	v_cndmask_b32_e64 v244, v246, v244, vcc
	s_nop 0
	v_cndmask_b32_e64 v245, v246, v245, s[98:99]
	s_add_i32 s36, s36, 1
	s_cmp_lt_i32 s36, s33
	s_waitcnt lgkmcnt(0)
	v_mfma_f32_16x16x32_bf16 v[16:19], v[214:217], v[20:23], v[16:19]
	v_mfma_f32_16x16x32_bf16 v[12:15], v[218:221], v[20:23], v[12:15]
	v_mfma_f32_16x16x32_bf16 v[8:11], v[222:225], v[20:23], v[8:11]
	v_mfma_f32_16x16x32_bf16 v[4:7], v[226:229], v[20:23], v[4:7]
	s_cbranch_scc1 .LBB0_565
	s_cmp_eq_u32 s3, 1
	s_cselect_b64 s[44:45], -1, 0
	s_cmp_lg_u32 s3, 1
	s_cbranch_scc1 .LBB0_582
.LBB0_567:
	s_add_i32 s0, s2, 16
	s_ashr_i32 s0, s0, 1
	s_max_i32 s26, s0, 0
	s_and_b64 s[0:1], s[38:39], exec
	s_cselect_b32 s0, 0, s26
	s_add_i32 s1, s2, 28
	s_ashr_i32 s1, s1, 1
	s_min_i32 s1, s1, 15
	s_and_b64 s[26:27], s[38:39], exec
	s_cselect_b32 s33, s1, 15
	s_cmp_gt_i32 s0, s33
	s_cbranch_scc1 .LBB0_570
	v_lshrrev_b32_e32 v2, 1, v95
	s_lshl_b32 s1, s0, 1
	s_add_i32 s36, s0, -1
	v_or_b32_e32 v0, s1, v2
	v_sub_u32_e32 v2, v88, v2
	s_lshl_b32 s0, s0, 6
	v_sub_u32_e32 v0, v0, v88
	v_subrev_u32_e32 v2, s1, v2
	v_add3_u32 v3, v92, s0, v94
	s_add_i32 s0, 0, 0x9000
	v_mov_b32_e32 v20, 0
	v_subrev_u32_e32 v0, 28, v0
	v_add_u32_e32 v2, 28, v2
	v_add3_u32 v3, v3, v93, s0
	v_mov_b32_e32 v21, v20
	v_mov_b32_e32 v22, v20
	v_mov_b32_e32 v23, v20
	v_mov_b32_e32 v24, v20
	v_mov_b32_e32 v25, v20
	v_mov_b32_e32 v26, v20
	v_mov_b32_e32 v27, v20
	v_mov_b32_e32 v28, v20
	v_mov_b32_e32 v29, v20
	v_mov_b32_e32 v30, v20
	v_mov_b32_e32 v31, v20
	v_mov_b32_e32 v32, v20
	v_mov_b32_e32 v33, v20
	v_mov_b32_e32 v34, v20
	v_mov_b32_e32 v35, v20
	v_add_u32_e32 v234, 12, v0
	v_add_u32_e32 v238, -12, v2
	v_cndmask_b32_e64 v230, v234, v238, s[38:39]
	v_max_i32_e32 v242, 0, v230
	v_lshl_add_u32 v242, v242, 9, v91
	v_add_u32_e32 v235, 8, v0
	v_add_u32_e32 v239, -8, v2
	v_cndmask_b32_e64 v231, v235, v239, s[38:39]
	v_max_i32_e32 v243, 0, v231
	v_lshl_add_u32 v243, v243, 9, v91
	v_add_u32_e32 v236, 4, v0
	v_add_u32_e32 v240, -4, v2
	v_cndmask_b32_e64 v232, v236, v240, s[38:39]
	v_max_i32_e32 v244, 0, v232
	v_lshl_add_u32 v244, v244, 9, v91
	v_cndmask_b32_e64 v233, v0, v2, s[38:39]
	v_max_i32_e32 v245, 0, v233
	v_lshl_add_u32 v245, v245, 9, v91
	v_cmp_lt_i32_e64 s[98:99], -1, v230
	v_cmp_lt_i32_e64 s[100:101], -1, v231
	v_cmp_lt_i32_e64 vcc, -1, v232
	v_cndmask_b32_e64 v242, v246, v242, s[98:99]
	v_cmp_lt_i32_e64 s[98:99], -1, v233
	v_cndmask_b32_e64 v243, v246, v243, s[100:101]
	v_cndmask_b32_e64 v244, v246, v244, vcc
	s_nop 0
	v_cndmask_b32_e64 v245, v246, v245, s[98:99]
.LBB0_569:
	ds_read_b128 v[214:217], v242 offset:4096
	ds_read_b128 v[218:221], v243 offset:4096
	ds_read_b128 v[222:225], v244 offset:4096
	ds_read_b128 v[226:229], v245 offset:4096
	ds_read_b128 v[36:39], v3
	v_add_u32_e32 v0, 2, v0
	v_add_u32_e32 v2, -2, v2
	v_add_u32_e32 v3, 64, v3
	v_add_u32_e32 v234, 12, v0
	v_add_u32_e32 v238, -12, v2
	v_cndmask_b32_e64 v230, v234, v238, s[38:39]
	v_max_i32_e32 v242, 0, v230
	v_lshl_add_u32 v242, v242, 9, v91
	v_add_u32_e32 v235, 8, v0
	v_add_u32_e32 v239, -8, v2
	v_cndmask_b32_e64 v231, v235, v239, s[38:39]
	v_max_i32_e32 v243, 0, v231
	v_lshl_add_u32 v243, v243, 9, v91
	v_add_u32_e32 v236, 4, v0
	v_add_u32_e32 v240, -4, v2
	v_cndmask_b32_e64 v232, v236, v240, s[38:39]
	v_max_i32_e32 v244, 0, v232
	v_lshl_add_u32 v244, v244, 9, v91
	v_cndmask_b32_e64 v233, v0, v2, s[38:39]
	v_max_i32_e32 v245, 0, v233
	v_lshl_add_u32 v245, v245, 9, v91
	v_cmp_lt_i32_e64 s[98:99], -1, v230
	v_cmp_lt_i32_e64 s[100:101], -1, v231
	v_cmp_lt_i32_e64 vcc, -1, v232
	v_cndmask_b32_e64 v242, v246, v242, s[98:99]
	v_cmp_lt_i32_e64 s[98:99], -1, v233
	v_cndmask_b32_e64 v243, v246, v243, s[100:101]
	v_cndmask_b32_e64 v244, v246, v244, vcc
	s_nop 0
	v_cndmask_b32_e64 v245, v246, v245, s[98:99]
	s_add_i32 s36, s36, 1
	s_cmp_lt_i32 s36, s33
	s_waitcnt lgkmcnt(0)
	v_mfma_f32_16x16x32_bf16 v[32:35], v[214:217], v[36:39], v[32:35]
	v_mfma_f32_16x16x32_bf16 v[28:31], v[218:221], v[36:39], v[28:31]
	v_mfma_f32_16x16x32_bf16 v[24:27], v[222:225], v[36:39], v[24:27]
	v_mfma_f32_16x16x32_bf16 v[20:23], v[226:229], v[36:39], v[20:23]
	s_cbranch_scc1 .LBB0_569
	s_branch .LBB0_571

.LBB0_572:
	s_add_i32 s0, s2, 32
	s_ashr_i32 s0, s0, 1
	s_max_i32 s26, s0, 0
	s_and_b64 s[0:1], s[38:39], exec
	s_cselect_b32 s0, 0, s26
	s_add_i32 s1, s2, 44
	s_ashr_i32 s1, s1, 1
	s_min_i32 s1, s1, 15
	s_and_b64 s[26:27], s[38:39], exec
	s_cselect_b32 s33, s1, 15
	s_cmp_gt_i32 s0, s33
	s_cbranch_scc1 .LBB0_575
	v_lshrrev_b32_e32 v2, 1, v95
	s_lshl_b32 s1, s0, 1
	s_add_i32 s36, s0, -1
	v_or_b32_e32 v0, s1, v2
	v_sub_u32_e32 v2, v88, v2
	s_lshl_b32 s0, s0, 6
	v_sub_u32_e32 v0, v0, v88
	v_subrev_u32_e32 v2, s1, v2
	v_add3_u32 v3, v92, s0, v94
	s_add_i32 s0, 0, 0x9000
	v_mov_b32_e32 v36, 0
	v_subrev_u32_e32 v0, 44, v0
	v_add_u32_e32 v2, 44, v2
	v_add3_u32 v3, v3, v93, s0
	v_mov_b32_e32 v37, v36
	v_mov_b32_e32 v38, v36
	v_mov_b32_e32 v39, v36
	v_mov_b32_e32 v44, v36
	v_mov_b32_e32 v45, v36
	v_mov_b32_e32 v46, v36
	v_mov_b32_e32 v47, v36
	v_mov_b32_e32 v52, v36
	v_mov_b32_e32 v53, v36
	v_mov_b32_e32 v54, v36
	v_mov_b32_e32 v55, v36
	v_mov_b32_e32 v56, v36
	v_mov_b32_e32 v57, v36
	v_mov_b32_e32 v58, v36
	v_mov_b32_e32 v59, v36
	v_add_u32_e32 v234, 12, v0
	v_add_u32_e32 v238, -12, v2
	v_cndmask_b32_e64 v230, v234, v238, s[38:39]
	v_max_i32_e32 v242, 0, v230
	v_lshl_add_u32 v242, v242, 9, v91
	v_add_u32_e32 v235, 8, v0
	v_add_u32_e32 v239, -8, v2
	v_cndmask_b32_e64 v231, v235, v239, s[38:39]
	v_max_i32_e32 v243, 0, v231
	v_lshl_add_u32 v243, v243, 9, v91
	v_add_u32_e32 v236, 4, v0
	v_add_u32_e32 v240, -4, v2
	v_cndmask_b32_e64 v232, v236, v240, s[38:39]
	v_max_i32_e32 v244, 0, v232
	v_lshl_add_u32 v244, v244, 9, v91
	v_cndmask_b32_e64 v233, v0, v2, s[38:39]
	v_max_i32_e32 v245, 0, v233
	v_lshl_add_u32 v245, v245, 9, v91
	v_cmp_lt_i32_e64 s[98:99], -1, v230
	v_cmp_lt_i32_e64 s[100:101], -1, v231
	v_cmp_lt_i32_e64 vcc, -1, v232
	v_cndmask_b32_e64 v242, v246, v242, s[98:99]
	v_cmp_lt_i32_e64 s[98:99], -1, v233
	v_cndmask_b32_e64 v243, v246, v243, s[100:101]
	v_cndmask_b32_e64 v244, v246, v244, vcc
	s_nop 0
	v_cndmask_b32_e64 v245, v246, v245, s[98:99]
.LBB0_574:
	ds_read_b128 v[214:217], v242 offset:4096
	ds_read_b128 v[218:221], v243 offset:4096
	ds_read_b128 v[222:225], v244 offset:4096
	ds_read_b128 v[226:229], v245 offset:4096
	ds_read_b128 v[68:71], v3
	v_add_u32_e32 v0, 2, v0
	v_add_u32_e32 v2, -2, v2
	v_add_u32_e32 v3, 64, v3
	v_add_u32_e32 v234, 12, v0
	v_add_u32_e32 v238, -12, v2
	v_cndmask_b32_e64 v230, v234, v238, s[38:39]
	v_max_i32_e32 v242, 0, v230
	v_lshl_add_u32 v242, v242, 9, v91
	v_add_u32_e32 v235, 8, v0
	v_add_u32_e32 v239, -8, v2
	v_cndmask_b32_e64 v231, v235, v239, s[38:39]
	v_max_i32_e32 v243, 0, v231
	v_lshl_add_u32 v243, v243, 9, v91
	v_add_u32_e32 v236, 4, v0
	v_add_u32_e32 v240, -4, v2
	v_cndmask_b32_e64 v232, v236, v240, s[38:39]
	v_max_i32_e32 v244, 0, v232
	v_lshl_add_u32 v244, v244, 9, v91
	v_cndmask_b32_e64 v233, v0, v2, s[38:39]
	v_max_i32_e32 v245, 0, v233
	v_lshl_add_u32 v245, v245, 9, v91
	v_cmp_lt_i32_e64 s[98:99], -1, v230
	v_cmp_lt_i32_e64 s[100:101], -1, v231
	v_cmp_lt_i32_e64 vcc, -1, v232
	v_cndmask_b32_e64 v242, v246, v242, s[98:99]
	v_cmp_lt_i32_e64 s[98:99], -1, v233
	v_cndmask_b32_e64 v243, v246, v243, s[100:101]
	v_cndmask_b32_e64 v244, v246, v244, vcc
	s_nop 0
	v_cndmask_b32_e64 v245, v246, v245, s[98:99]
	s_add_i32 s36, s36, 1
	s_cmp_lt_i32 s36, s33
	s_waitcnt lgkmcnt(0)
	v_mfma_f32_16x16x32_bf16 v[56:59], v[214:217], v[68:71], v[56:59]
	v_mfma_f32_16x16x32_bf16 v[52:55], v[218:221], v[68:71], v[52:55]
	v_mfma_f32_16x16x32_bf16 v[44:47], v[222:225], v[68:71], v[44:47]
	v_mfma_f32_16x16x32_bf16 v[36:39], v[226:229], v[68:71], v[36:39]
	s_cbranch_scc1 .LBB0_574
	s_branch .LBB0_576

.LBB0_577:
	s_add_i32 s0, s2, 48
	s_ashr_i32 s0, s0, 1
	s_max_i32 s3, s0, 0
	s_and_b64 s[0:1], s[38:39], exec
	s_cselect_b32 s0, 0, s3
	s_add_i32 s1, s2, 60
	s_ashr_i32 s1, s1, 1
	s_min_i32 s1, s1, 15
	s_and_b64 s[26:27], s[38:39], exec
	s_cselect_b32 s3, s1, 15
	s_cmp_gt_i32 s0, s3
	s_cbranch_scc1 .LBB0_580
	v_lshrrev_b32_e32 v2, 1, v95
	s_lshl_b32 s1, s0, 1
	s_add_i32 s33, s0, -1
	v_or_b32_e32 v0, s1, v2
	v_sub_u32_e32 v2, v88, v2
	s_lshl_b32 s0, s0, 6
	v_sub_u32_e32 v0, v0, v88
	v_subrev_u32_e32 v2, s1, v2
	v_add3_u32 v3, v92, s0, v94
	s_add_i32 s0, 0, 0x9000
	v_mov_b32_e32 v68, 0
	v_subrev_u32_e32 v0, 60, v0
	v_add_u32_e32 v2, 60, v2
	v_add3_u32 v3, v3, v93, s0
	v_mov_b32_e32 v69, v68
	v_mov_b32_e32 v70, v68
	v_mov_b32_e32 v71, v68
	v_mov_b32_e32 v72, v68
	v_mov_b32_e32 v73, v68
	v_mov_b32_e32 v74, v68
	v_mov_b32_e32 v75, v68
	v_mov_b32_e32 v76, v68
	v_mov_b32_e32 v77, v68
	v_mov_b32_e32 v78, v68
	v_mov_b32_e32 v79, v68
	v_mov_b32_e32 v80, v68
	v_mov_b32_e32 v81, v68
	v_mov_b32_e32 v82, v68
	v_mov_b32_e32 v83, v68
	v_add_u32_e32 v234, 12, v0
	v_add_u32_e32 v238, -12, v2
	v_cndmask_b32_e64 v230, v234, v238, s[38:39]
	v_max_i32_e32 v242, 0, v230
	v_lshl_add_u32 v242, v242, 9, v91
	v_add_u32_e32 v235, 8, v0
	v_add_u32_e32 v239, -8, v2
	v_cndmask_b32_e64 v231, v235, v239, s[38:39]
	v_max_i32_e32 v243, 0, v231
	v_lshl_add_u32 v243, v243, 9, v91
	v_add_u32_e32 v236, 4, v0
	v_add_u32_e32 v240, -4, v2
	v_cndmask_b32_e64 v232, v236, v240, s[38:39]
	v_max_i32_e32 v244, 0, v232
	v_lshl_add_u32 v244, v244, 9, v91
	v_cndmask_b32_e64 v233, v0, v2, s[38:39]
	v_max_i32_e32 v245, 0, v233
	v_lshl_add_u32 v245, v245, 9, v91
	v_cmp_lt_i32_e64 s[98:99], -1, v230
	v_cmp_lt_i32_e64 s[100:101], -1, v231
	v_cmp_lt_i32_e64 vcc, -1, v232
	v_cndmask_b32_e64 v242, v246, v242, s[98:99]
	v_cmp_lt_i32_e64 s[98:99], -1, v233
	v_cndmask_b32_e64 v243, v246, v243, s[100:101]
	v_cndmask_b32_e64 v244, v246, v244, vcc
	s_nop 0
	v_cndmask_b32_e64 v245, v246, v245, s[98:99]
.LBB0_579:
	ds_read_b128 v[214:217], v242 offset:4096
	ds_read_b128 v[218:221], v243 offset:4096
	ds_read_b128 v[222:225], v244 offset:4096
	ds_read_b128 v[226:229], v245 offset:4096
	ds_read_b128 v[84:87], v3
	v_add_u32_e32 v0, 2, v0
	v_add_u32_e32 v2, -2, v2
	v_add_u32_e32 v3, 64, v3
	v_add_u32_e32 v234, 12, v0
	v_add_u32_e32 v238, -12, v2
	v_cndmask_b32_e64 v230, v234, v238, s[38:39]
	v_max_i32_e32 v242, 0, v230
	v_lshl_add_u32 v242, v242, 9, v91
	v_add_u32_e32 v235, 8, v0
	v_add_u32_e32 v239, -8, v2
	v_cndmask_b32_e64 v231, v235, v239, s[38:39]
	v_max_i32_e32 v243, 0, v231
	v_lshl_add_u32 v243, v243, 9, v91
	v_add_u32_e32 v236, 4, v0
	v_add_u32_e32 v240, -4, v2
	v_cndmask_b32_e64 v232, v236, v240, s[38:39]
	v_max_i32_e32 v244, 0, v232
	v_lshl_add_u32 v244, v244, 9, v91
	v_cndmask_b32_e64 v233, v0, v2, s[38:39]
	v_max_i32_e32 v245, 0, v233
	v_lshl_add_u32 v245, v245, 9, v91
	v_cmp_lt_i32_e64 s[98:99], -1, v230
	v_cmp_lt_i32_e64 s[100:101], -1, v231
	v_cmp_lt_i32_e64 vcc, -1, v232
	v_cndmask_b32_e64 v242, v246, v242, s[98:99]
	v_cmp_lt_i32_e64 s[98:99], -1, v233
	v_cndmask_b32_e64 v243, v246, v243, s[100:101]
	v_cndmask_b32_e64 v244, v246, v244, vcc
	s_nop 0
	v_cndmask_b32_e64 v245, v246, v245, s[98:99]
	s_add_i32 s33, s33, 1
	s_cmp_lt_i32 s33, s3
	s_waitcnt lgkmcnt(0)
	v_mfma_f32_16x16x32_bf16 v[80:83], v[214:217], v[84:87], v[80:83]
	v_mfma_f32_16x16x32_bf16 v[76:79], v[218:221], v[84:87], v[76:79]
	v_mfma_f32_16x16x32_bf16 v[72:75], v[222:225], v[84:87], v[72:75]
	v_mfma_f32_16x16x32_bf16 v[68:71], v[226:229], v[84:87], v[68:71]
	s_cbranch_scc1 .LBB0_579
	s_branch .LBB0_585

.LBB0_585:
	v_cndmask_b32_e64 v0, 0, 1, s[42:43]
	v_cmp_ne_u32_e64 s[40:41], 1, v0
	s_andn2_b64 vcc, exec, s[42:43]
	s_barrier
	s_waitcnt vmcnt(3)
	ds_write_b128 v96, v[40:43] offset:36864
	s_waitcnt vmcnt(2)
	ds_write_b128 v96, v[48:51] offset:41088
	s_waitcnt vmcnt(1)
	ds_write_b128 v96, v[60:63] offset:45312
	s_waitcnt vmcnt(0)
	ds_write_b128 v96, v[64:67] offset:49536
	s_waitcnt lgkmcnt(0)
	s_barrier
	s_cbranch_vccnz .LBB0_589
	s_ashr_i32 s0, s2, 1
	s_max_i32 s3, s0, 16
	s_and_b64 s[0:1], s[38:39], exec
	s_cselect_b32 s0, 16, s3
	s_add_i32 s1, s2, 12
	s_ashr_i32 s1, s1, 1
	s_min_i32 s1, s1, 31
	s_and_b64 s[26:27], s[38:39], exec
	s_cselect_b32 s3, s1, 31
	s_cmp_gt_i32 s0, s3
	s_cbranch_scc1 .LBB0_589
	v_lshrrev_b32_e32 v2, 1, v95
	s_lshl_b32 s1, s0, 1
	s_add_i32 s33, s0, -1
	v_or_b32_e32 v0, s1, v2
	s_lshl_b32 s0, s0, 6
	v_sub_u32_e32 v0, v0, v88
	v_sub_u32_e32 v2, v88, v2
	v_add3_u32 v3, v92, s0, v94
	v_readlane_b32 s0, v253, 42
	v_add_u32_e32 v0, -12, v0
	v_subrev_u32_e32 v2, s1, v2
	v_add3_u32 v3, v3, v93, s0
	v_add_u32_e32 v234, 12, v0
	v_cndmask_b32_e64 v230, v234, v2, s[38:39]
	v_max_i32_e32 v242, 0, v230
	v_lshl_add_u32 v242, v242, 9, v91
	v_add_u32_e32 v235, 8, v0
	v_add_u32_e32 v239, 4, v2
	v_cndmask_b32_e64 v231, v235, v239, s[38:39]
	v_max_i32_e32 v243, 0, v231
	v_lshl_add_u32 v243, v243, 9, v91
	v_add_u32_e32 v236, 4, v0
	v_add_u32_e32 v240, 8, v2
	v_cndmask_b32_e64 v232, v236, v240, s[38:39]
	v_max_i32_e32 v244, 0, v232
	v_lshl_add_u32 v244, v244, 9, v91
	v_add_u32_e32 v241, 12, v2
	v_cndmask_b32_e64 v233, v0, v241, s[38:39]
	v_max_i32_e32 v245, 0, v233
	v_lshl_add_u32 v245, v245, 9, v91
	v_cmp_lt_i32_e64 s[98:99], -1, v230
	v_cmp_lt_i32_e64 s[100:101], -1, v231
	v_cmp_lt_i32_e64 vcc, -1, v232
	v_cndmask_b32_e64 v242, v246, v242, s[98:99]
	v_cmp_lt_i32_e64 s[98:99], -1, v233
	v_cndmask_b32_e64 v243, v246, v243, s[100:101]
	v_cndmask_b32_e64 v244, v246, v244, vcc
	s_nop 0
	v_cndmask_b32_e64 v245, v246, v245, s[98:99]
.LBB0_588:
	ds_read_b128 v[214:217], v242 offset:4096
	ds_read_b128 v[218:221], v243 offset:4096
	ds_read_b128 v[222:225], v244 offset:4096
	ds_read_b128 v[226:229], v245 offset:4096
	ds_read_b128 v[40:43], v3
	v_add_u32_e32 v0, 2, v0
	v_add_u32_e32 v2, -2, v2
	v_add_u32_e32 v3, 64, v3
	v_add_u32_e32 v234, 12, v0
	v_cndmask_b32_e64 v230, v234, v2, s[38:39]
	v_max_i32_e32 v242, 0, v230
	v_lshl_add_u32 v242, v242, 9, v91
	v_add_u32_e32 v235, 8, v0
	v_add_u32_e32 v239, 4, v2
	v_cndmask_b32_e64 v231, v235, v239, s[38:39]
	v_max_i32_e32 v243, 0, v231
	v_lshl_add_u32 v243, v243, 9, v91
	v_add_u32_e32 v236, 4, v0
	v_add_u32_e32 v240, 8, v2
	v_cndmask_b32_e64 v232, v236, v240, s[38:39]
	v_max_i32_e32 v244, 0, v232
	v_lshl_add_u32 v244, v244, 9, v91
	v_add_u32_e32 v241, 12, v2
	v_cndmask_b32_e64 v233, v0, v241, s[38:39]
	v_max_i32_e32 v245, 0, v233
	v_lshl_add_u32 v245, v245, 9, v91
	v_cmp_lt_i32_e64 s[98:99], -1, v230
	v_cmp_lt_i32_e64 s[100:101], -1, v231
	v_cmp_lt_i32_e64 vcc, -1, v232
	v_cndmask_b32_e64 v242, v246, v242, s[98:99]
	v_cmp_lt_i32_e64 s[98:99], -1, v233
	v_cndmask_b32_e64 v243, v246, v243, s[100:101]
	v_cndmask_b32_e64 v244, v246, v244, vcc
	s_nop 0
	v_cndmask_b32_e64 v245, v246, v245, s[98:99]
	s_add_i32 s33, s33, 1
	s_cmp_lt_i32 s33, s3
	s_waitcnt lgkmcnt(0)
	v_mfma_f32_16x16x32_bf16 v[16:19], v[214:217], v[40:43], v[16:19]
	v_mfma_f32_16x16x32_bf16 v[12:15], v[218:221], v[40:43], v[12:15]
	v_mfma_f32_16x16x32_bf16 v[8:11], v[222:225], v[40:43], v[8:11]
	v_mfma_f32_16x16x32_bf16 v[4:7], v[226:229], v[40:43], v[4:7]
	s_cbranch_scc1 .LBB0_588
.LBB0_589:
	v_cndmask_b32_e64 v0, 0, 1, s[44:45]
	v_cmp_ne_u32_e64 s[42:43], 1, v0
	s_andn2_b64 vcc, exec, s[44:45]
	s_cbranch_vccnz .LBB0_593
	s_add_i32 s0, s2, 16
	s_ashr_i32 s0, s0, 1
	s_max_i32 s3, s0, 16
	s_and_b64 s[0:1], s[38:39], exec
	s_cselect_b32 s0, 16, s3
	s_add_i32 s1, s2, 28
	s_ashr_i32 s1, s1, 1
	s_min_i32 s1, s1, 31
	s_and_b64 s[26:27], s[38:39], exec
	s_cselect_b32 s3, s1, 31
	s_cmp_gt_i32 s0, s3
	s_cbranch_scc1 .LBB0_593
	v_lshrrev_b32_e32 v2, 1, v95
	s_lshl_b32 s1, s0, 1
	s_add_i32 s33, s0, -1
	v_or_b32_e32 v0, s1, v2
	v_sub_u32_e32 v2, v88, v2
	s_lshl_b32 s0, s0, 6
	v_sub_u32_e32 v0, v0, v88
	v_subrev_u32_e32 v2, s1, v2
	v_add3_u32 v3, v92, s0, v94
	v_readlane_b32 s0, v253, 42
	v_subrev_u32_e32 v0, 28, v0
	v_add_u32_e32 v2, 28, v2
	v_add3_u32 v3, v3, v93, s0
	v_add_u32_e32 v234, 12, v0
	v_add_u32_e32 v238, -12, v2
	v_cndmask_b32_e64 v230, v234, v238, s[38:39]
	v_max_i32_e32 v242, 0, v230
	v_lshl_add_u32 v242, v242, 9, v91
	v_add_u32_e32 v235, 8, v0
	v_add_u32_e32 v239, -8, v2
	v_cndmask_b32_e64 v231, v235, v239, s[38:39]
	v_max_i32_e32 v243, 0, v231
	v_lshl_add_u32 v243, v243, 9, v91
	v_add_u32_e32 v236, 4, v0
	v_add_u32_e32 v240, -4, v2
	v_cndmask_b32_e64 v232, v236, v240, s[38:39]
	v_max_i32_e32 v244, 0, v232
	v_lshl_add_u32 v244, v244, 9, v91
	v_cndmask_b32_e64 v233, v0, v2, s[38:39]
	v_max_i32_e32 v245, 0, v233
	v_lshl_add_u32 v245, v245, 9, v91
	v_cmp_lt_i32_e64 s[98:99], -1, v230
	v_cmp_lt_i32_e64 s[100:101], -1, v231
	v_cmp_lt_i32_e64 vcc, -1, v232
	v_cndmask_b32_e64 v242, v246, v242, s[98:99]
	v_cmp_lt_i32_e64 s[98:99], -1, v233
	v_cndmask_b32_e64 v243, v246, v243, s[100:101]
	v_cndmask_b32_e64 v244, v246, v244, vcc
	s_nop 0
	v_cndmask_b32_e64 v245, v246, v245, s[98:99]
.LBB0_592:
	ds_read_b128 v[214:217], v242 offset:4096
	ds_read_b128 v[218:221], v243 offset:4096
	ds_read_b128 v[222:225], v244 offset:4096
	ds_read_b128 v[226:229], v245 offset:4096
	ds_read_b128 v[40:43], v3
	v_add_u32_e32 v0, 2, v0
	v_add_u32_e32 v2, -2, v2
	v_add_u32_e32 v3, 64, v3
	v_add_u32_e32 v234, 12, v0
	v_add_u32_e32 v238, -12, v2
	v_cndmask_b32_e64 v230, v234, v238, s[38:39]
	v_max_i32_e32 v242, 0, v230
	v_lshl_add_u32 v242, v242, 9, v91
	v_add_u32_e32 v235, 8, v0
	v_add_u32_e32 v239, -8, v2
	v_cndmask_b32_e64 v231, v235, v239, s[38:39]
	v_max_i32_e32 v243, 0, v231
	v_lshl_add_u32 v243, v243, 9, v91
	v_add_u32_e32 v236, 4, v0
	v_add_u32_e32 v240, -4, v2
	v_cndmask_b32_e64 v232, v236, v240, s[38:39]
	v_max_i32_e32 v244, 0, v232
	v_lshl_add_u32 v244, v244, 9, v91
	v_cndmask_b32_e64 v233, v0, v2, s[38:39]
	v_max_i32_e32 v245, 0, v233
	v_lshl_add_u32 v245, v245, 9, v91
	v_cmp_lt_i32_e64 s[98:99], -1, v230
	v_cmp_lt_i32_e64 s[100:101], -1, v231
	v_cmp_lt_i32_e64 vcc, -1, v232
	v_cndmask_b32_e64 v242, v246, v242, s[98:99]
	v_cmp_lt_i32_e64 s[98:99], -1, v233
	v_cndmask_b32_e64 v243, v246, v243, s[100:101]
	v_cndmask_b32_e64 v244, v246, v244, vcc
	s_nop 0
	v_cndmask_b32_e64 v245, v246, v245, s[98:99]
	s_add_i32 s33, s33, 1
	s_cmp_lt_i32 s33, s3
	s_waitcnt lgkmcnt(0)
	v_mfma_f32_16x16x32_bf16 v[32:35], v[214:217], v[40:43], v[32:35]
	v_mfma_f32_16x16x32_bf16 v[28:31], v[218:221], v[40:43], v[28:31]
	v_mfma_f32_16x16x32_bf16 v[24:27], v[222:225], v[40:43], v[24:27]
	v_mfma_f32_16x16x32_bf16 v[20:23], v[226:229], v[40:43], v[20:23]
	s_cbranch_scc1 .LBB0_592
.LBB0_593:
	v_cndmask_b32_e64 v0, 0, 1, s[46:47]
	v_cmp_ne_u32_e64 s[44:45], 1, v0
	s_andn2_b64 vcc, exec, s[46:47]
	s_cbranch_vccnz .LBB0_597
	s_add_i32 s0, s2, 32
	s_ashr_i32 s0, s0, 1
	s_max_i32 s3, s0, 16
	s_and_b64 s[0:1], s[38:39], exec
	s_cselect_b32 s0, 16, s3
	s_add_i32 s1, s2, 44
	s_ashr_i32 s1, s1, 1
	s_min_i32 s1, s1, 31
	s_and_b64 s[26:27], s[38:39], exec
	s_cselect_b32 s3, s1, 31
	s_cmp_gt_i32 s0, s3
	s_cbranch_scc1 .LBB0_597
	v_lshrrev_b32_e32 v2, 1, v95
	s_lshl_b32 s1, s0, 1
	s_add_i32 s33, s0, -1
	v_or_b32_e32 v0, s1, v2
	v_sub_u32_e32 v2, v88, v2
	s_lshl_b32 s0, s0, 6
	v_sub_u32_e32 v0, v0, v88
	v_subrev_u32_e32 v2, s1, v2
	v_add3_u32 v3, v92, s0, v94
	v_readlane_b32 s0, v253, 42
	v_subrev_u32_e32 v0, 44, v0
	v_add_u32_e32 v2, 44, v2
	v_add3_u32 v3, v3, v93, s0
	v_add_u32_e32 v234, 12, v0
	v_add_u32_e32 v238, -12, v2
	v_cndmask_b32_e64 v230, v234, v238, s[38:39]
	v_max_i32_e32 v242, 0, v230
	v_lshl_add_u32 v242, v242, 9, v91
	v_add_u32_e32 v235, 8, v0
	v_add_u32_e32 v239, -8, v2
	v_cndmask_b32_e64 v231, v235, v239, s[38:39]
	v_max_i32_e32 v243, 0, v231
	v_lshl_add_u32 v243, v243, 9, v91
	v_add_u32_e32 v236, 4, v0
	v_add_u32_e32 v240, -4, v2
	v_cndmask_b32_e64 v232, v236, v240, s[38:39]
	v_max_i32_e32 v244, 0, v232
	v_lshl_add_u32 v244, v244, 9, v91
	v_cndmask_b32_e64 v233, v0, v2, s[38:39]
	v_max_i32_e32 v245, 0, v233
	v_lshl_add_u32 v245, v245, 9, v91
	v_cmp_lt_i32_e64 s[98:99], -1, v230
	v_cmp_lt_i32_e64 s[100:101], -1, v231
	v_cmp_lt_i32_e64 vcc, -1, v232
	v_cndmask_b32_e64 v242, v246, v242, s[98:99]
	v_cmp_lt_i32_e64 s[98:99], -1, v233
	v_cndmask_b32_e64 v243, v246, v243, s[100:101]
	v_cndmask_b32_e64 v244, v246, v244, vcc
	s_nop 0
	v_cndmask_b32_e64 v245, v246, v245, s[98:99]
.LBB0_596:
	ds_read_b128 v[214:217], v242 offset:4096
	ds_read_b128 v[218:221], v243 offset:4096
	ds_read_b128 v[222:225], v244 offset:4096
	ds_read_b128 v[226:229], v245 offset:4096
	ds_read_b128 v[40:43], v3
	v_add_u32_e32 v0, 2, v0
	v_add_u32_e32 v2, -2, v2
	v_add_u32_e32 v3, 64, v3
	v_add_u32_e32 v234, 12, v0
	v_add_u32_e32 v238, -12, v2
	v_cndmask_b32_e64 v230, v234, v238, s[38:39]
	v_max_i32_e32 v242, 0, v230
	v_lshl_add_u32 v242, v242, 9, v91
	v_add_u32_e32 v235, 8, v0
	v_add_u32_e32 v239, -8, v2
	v_cndmask_b32_e64 v231, v235, v239, s[38:39]
	v_max_i32_e32 v243, 0, v231
	v_lshl_add_u32 v243, v243, 9, v91
	v_add_u32_e32 v236, 4, v0
	v_add_u32_e32 v240, -4, v2
	v_cndmask_b32_e64 v232, v236, v240, s[38:39]
	v_max_i32_e32 v244, 0, v232
	v_lshl_add_u32 v244, v244, 9, v91
	v_cndmask_b32_e64 v233, v0, v2, s[38:39]
	v_max_i32_e32 v245, 0, v233
	v_lshl_add_u32 v245, v245, 9, v91
	v_cmp_lt_i32_e64 s[98:99], -1, v230
	v_cmp_lt_i32_e64 s[100:101], -1, v231
	v_cmp_lt_i32_e64 vcc, -1, v232
	v_cndmask_b32_e64 v242, v246, v242, s[98:99]
	v_cmp_lt_i32_e64 s[98:99], -1, v233
	v_cndmask_b32_e64 v243, v246, v243, s[100:101]
	v_cndmask_b32_e64 v244, v246, v244, vcc
	s_nop 0
	v_cndmask_b32_e64 v245, v246, v245, s[98:99]
	s_add_i32 s33, s33, 1
	s_cmp_lt_i32 s33, s3
	s_waitcnt lgkmcnt(0)
	v_mfma_f32_16x16x32_bf16 v[56:59], v[214:217], v[40:43], v[56:59]
	v_mfma_f32_16x16x32_bf16 v[52:55], v[218:221], v[40:43], v[52:55]
	v_mfma_f32_16x16x32_bf16 v[44:47], v[222:225], v[40:43], v[44:47]
	v_mfma_f32_16x16x32_bf16 v[36:39], v[226:229], v[40:43], v[36:39]
	s_cbranch_scc1 .LBB0_596
.LBB0_597:
	v_cndmask_b32_e64 v0, 0, 1, s[52:53]
	v_cmp_ne_u32_e64 s[46:47], 1, v0
	s_andn2_b64 vcc, exec, s[52:53]
	s_cbranch_vccnz .LBB0_601
	s_add_i32 s0, s2, 48
	s_ashr_i32 s0, s0, 1
	s_max_i32 s3, s0, 16
	s_and_b64 s[0:1], s[38:39], exec
	s_cselect_b32 s0, 16, s3
	s_add_i32 s2, s2, 60
	s_ashr_i32 s1, s2, 1
	s_min_i32 s1, s1, 31
	s_and_b64 s[2:3], s[38:39], exec
	s_cselect_b32 s2, s1, 31
	s_cmp_gt_i32 s0, s2
	s_cbranch_scc1 .LBB0_601
	v_lshrrev_b32_e32 v2, 1, v95
	s_lshl_b32 s1, s0, 1
	s_add_i32 s3, s0, -1
	v_or_b32_e32 v0, s1, v2
	v_sub_u32_e32 v2, v88, v2
	s_lshl_b32 s0, s0, 6
	v_sub_u32_e32 v0, v0, v88
	v_subrev_u32_e32 v2, s1, v2
	v_add3_u32 v3, v92, s0, v94
	v_readlane_b32 s0, v253, 42
	v_subrev_u32_e32 v0, 60, v0
	v_add_u32_e32 v2, 60, v2
	v_add3_u32 v3, v3, v93, s0
	v_add_u32_e32 v234, 12, v0
	v_add_u32_e32 v238, -12, v2
	v_cndmask_b32_e64 v230, v234, v238, s[38:39]
	v_max_i32_e32 v242, 0, v230
	v_lshl_add_u32 v242, v242, 9, v91
	v_add_u32_e32 v235, 8, v0
	v_add_u32_e32 v239, -8, v2
	v_cndmask_b32_e64 v231, v235, v239, s[38:39]
	v_max_i32_e32 v243, 0, v231
	v_lshl_add_u32 v243, v243, 9, v91
	v_add_u32_e32 v236, 4, v0
	v_add_u32_e32 v240, -4, v2
	v_cndmask_b32_e64 v232, v236, v240, s[38:39]
	v_max_i32_e32 v244, 0, v232
	v_lshl_add_u32 v244, v244, 9, v91
	v_cndmask_b32_e64 v233, v0, v2, s[38:39]
	v_max_i32_e32 v245, 0, v233
	v_lshl_add_u32 v245, v245, 9, v91
	v_cmp_lt_i32_e64 s[98:99], -1, v230
	v_cmp_lt_i32_e64 s[100:101], -1, v231
	v_cmp_lt_i32_e64 vcc, -1, v232
	v_cndmask_b32_e64 v242, v246, v242, s[98:99]
	v_cmp_lt_i32_e64 s[98:99], -1, v233
	v_cndmask_b32_e64 v243, v246, v243, s[100:101]
	v_cndmask_b32_e64 v244, v246, v244, vcc
	s_nop 0
	v_cndmask_b32_e64 v245, v246, v245, s[98:99]
.LBB0_600:
	ds_read_b128 v[214:217], v242 offset:4096
	ds_read_b128 v[218:221], v243 offset:4096
	ds_read_b128 v[222:225], v244 offset:4096
	ds_read_b128 v[226:229], v245 offset:4096
	ds_read_b128 v[40:43], v3
	v_add_u32_e32 v0, 2, v0
	v_add_u32_e32 v2, -2, v2
	v_add_u32_e32 v3, 64, v3
	v_add_u32_e32 v234, 12, v0
	v_add_u32_e32 v238, -12, v2
	v_cndmask_b32_e64 v230, v234, v238, s[38:39]
	v_max_i32_e32 v242, 0, v230
	v_lshl_add_u32 v242, v242, 9, v91
	v_add_u32_e32 v235, 8, v0
	v_add_u32_e32 v239, -8, v2
	v_cndmask_b32_e64 v231, v235, v239, s[38:39]
	v_max_i32_e32 v243, 0, v231
	v_lshl_add_u32 v243, v243, 9, v91
	v_add_u32_e32 v236, 4, v0
	v_add_u32_e32 v240, -4, v2
	v_cndmask_b32_e64 v232, v236, v240, s[38:39]
	v_max_i32_e32 v244, 0, v232
	v_lshl_add_u32 v244, v244, 9, v91
	v_cndmask_b32_e64 v233, v0, v2, s[38:39]
	v_max_i32_e32 v245, 0, v233
	v_lshl_add_u32 v245, v245, 9, v91
	v_cmp_lt_i32_e64 s[98:99], -1, v230
	v_cmp_lt_i32_e64 s[100:101], -1, v231
	v_cmp_lt_i32_e64 vcc, -1, v232
	v_cndmask_b32_e64 v242, v246, v242, s[98:99]
	v_cmp_lt_i32_e64 s[98:99], -1, v233
	v_cndmask_b32_e64 v243, v246, v243, s[100:101]
	v_cndmask_b32_e64 v244, v246, v244, vcc
	s_nop 0
	v_cndmask_b32_e64 v245, v246, v245, s[98:99]
	s_add_i32 s3, s3, 1
	s_cmp_lt_i32 s3, s2
	s_waitcnt lgkmcnt(0)
	v_mfma_f32_16x16x32_bf16 v[80:83], v[214:217], v[40:43], v[80:83]
	v_mfma_f32_16x16x32_bf16 v[76:79], v[218:221], v[40:43], v[76:79]
	v_mfma_f32_16x16x32_bf16 v[72:75], v[222:225], v[40:43], v[72:75]
	v_mfma_f32_16x16x32_bf16 v[68:71], v[226:229], v[40:43], v[68:71]
	s_cbranch_scc1 .LBB0_600

.LBB0_715:
	s_or_b64 exec, exec, s[40:41]
	s_waitcnt vmcnt(31)
	v_and_b32_e32 v93, 15, v50
	v_or_b32_e32 v18, s2, v93
	v_mul_lo_u16_sdwa v0, v18, v204 dst_sel:DWORD dst_unused:UNUSED_PAD src0_sel:BYTE_0 src1_sel:DWORD
	v_lshrrev_b16_e32 v0, 11, v0
	v_mul_lo_u16_e32 v19, 36, v0
	v_sub_u16_e32 v18, v18, v19
	v_cmp_gt_u16_sdwa s[0:1], v18, v205 src0_sel:BYTE_0 src1_sel:DWORD
	v_lshlrev_b32_sdwa v18, v206, v18 dst_sel:DWORD dst_unused:UNUSED_PAD src0_sel:DWORD src1_sel:BYTE_0
	s_and_saveexec_b64 s[2:3], s[0:1]
	s_xor_b64 s[38:39], exec, s[2:3]
	v_lshlrev_b32_e32 v0, 11, v0
	s_movk_i32 s0, 0xff00
	v_add3_u32 v100, v0, v18, s0
	s_andn2_saveexec_b64 s[38:39], s[38:39]
	v_lshlrev_b32_e32 v0, 8, v0
	v_or3_b32 v100, v0, v18, s74
	s_or_b64 exec, exec, s[38:39]
	v_readfirstlane_b32 s41, v88
	s_movk_i32 s0, 0x420
	s_ashr_i32 s2, s41, 1
	v_mad_u32_u24 v18, v93, s0, 0
	v_lshlrev_b32_e32 v19, 10, v93
	s_max_i32 s3, s2, 0
	v_sub_u32_e32 v95, v18, v19
	v_mul_lo_u32 v18, v88, s0
	s_and_b64 s[0:1], vcc, exec
	s_cselect_b32 s0, 0, s3
	s_add_i32 s1, s41, 12
	s_ashr_i32 s3, s1, 1
	v_bfe_u32 v0, v50, 4, 2
	v_lshlrev_b32_e32 v19, 4, v50
	s_min_i32 s1, s3, 15
	v_lshlrev_b32_e32 v90, 4, v0
	v_and_b32_e32 v20, 0x3e0, v19
	s_and_b64 s[26:27], vcc, exec
	v_and_b32_e32 v97, 16, v90
	v_add3_u32 v18, 0, v18, v20
	v_and_b32_e32 v19, 16, v19
	s_cselect_b32 s19, s1, 15
	v_lshrrev_b32_e32 v101, 1, v0
	v_mul_u32_u24_e32 v91, 0x420, v93
	v_and_b32_e32 v99, 32, v90
	s_waitcnt vmcnt(29)
	v_add_u32_e32 v89, v95, v97
	v_add_u32_e32 v94, v18, v19
	s_cmp_gt_i32 s0, s19
	v_sub_u32_e32 v92, v88, v101
	s_waitcnt lgkmcnt(0)
	s_barrier
	s_waitcnt vmcnt(7)
	ds_write_b128 v94, v[2:5] offset:36864
	s_waitcnt vmcnt(6)
	ds_write_b128 v94, v[6:9] offset:41088
	s_waitcnt vmcnt(5)
	ds_write_b128 v94, v[10:13] offset:45312
	s_waitcnt vmcnt(4)
	ds_write_b128 v94, v[14:17] offset:49536
	s_waitcnt lgkmcnt(0)
	s_barrier
	s_cbranch_scc1 .LBB0_722
	s_lshl_b32 s1, s0, 1
	s_add_i32 s33, s0, -1
	v_or_b32_e32 v0, s1, v101
	s_lshl_b32 s0, s0, 6
	v_sub_u32_e32 v0, v0, v88
	v_add3_u32 v3, v91, s0, v99
	s_add_i32 s0, 0, 0x9000
	v_mov_b32_e32 v4, 0
	v_add_u32_e32 v0, -12, v0
	v_subrev_u32_e32 v2, s1, v92
	v_add3_u32 v3, v3, v97, s0
	v_mov_b32_e32 v5, v4
	v_mov_b32_e32 v6, v4
	v_mov_b32_e32 v7, v4
	v_mov_b32_e32 v8, v4
	v_mov_b32_e32 v9, v4
	v_mov_b32_e32 v10, v4
	v_mov_b32_e32 v11, v4
	v_mov_b32_e32 v12, v4
	v_mov_b32_e32 v13, v4
	v_mov_b32_e32 v14, v4
	v_mov_b32_e32 v15, v4
	v_mov_b32_e32 v16, v4
	v_mov_b32_e32 v17, v4
	v_mov_b32_e32 v18, v4
	v_mov_b32_e32 v19, v4
	v_add_u32_e32 v234, 12, v0
	v_cndmask_b32_e64 v230, v234, v2, vcc
	v_max_i32_e32 v242, 0, v230
	v_lshl_add_u32 v242, v242, 9, v89
	v_add_u32_e32 v235, 8, v0
	v_add_u32_e32 v239, 4, v2
	v_cndmask_b32_e64 v231, v235, v239, vcc
	v_max_i32_e32 v243, 0, v231
	v_lshl_add_u32 v243, v243, 9, v89
	v_add_u32_e32 v236, 4, v0
	v_add_u32_e32 v240, 8, v2
	v_cndmask_b32_e64 v232, v236, v240, vcc
	v_max_i32_e32 v244, 0, v232
	v_lshl_add_u32 v244, v244, 9, v89
	v_add_u32_e32 v241, 12, v2
	v_cndmask_b32_e64 v233, v0, v241, vcc
	v_max_i32_e32 v245, 0, v233
	v_lshl_add_u32 v245, v245, 9, v89
	v_cmp_lt_i32_e64 s[98:99], -1, v230
	v_cmp_lt_i32_e64 s[100:101], -1, v231
	v_cmp_lt_i32_e64 s[38:39], -1, v232
	v_cndmask_b32_e64 v242, v246, v242, s[98:99]
	v_cmp_lt_i32_e64 s[98:99], -1, v233
	v_cndmask_b32_e64 v243, v246, v243, s[100:101]
	v_cndmask_b32_e64 v244, v246, v244, s[38:39]
	s_nop 0
	v_cndmask_b32_e64 v245, v246, v245, s[98:99]
.LBB0_721:
	ds_read_b128 v[214:217], v242 offset:4096
	ds_read_b128 v[218:221], v243 offset:4096
	ds_read_b128 v[222:225], v244 offset:4096
	ds_read_b128 v[226:229], v245 offset:4096
	ds_read_b128 v[20:23], v3
	v_add_u32_e32 v0, 2, v0
	v_add_u32_e32 v2, -2, v2
	v_add_u32_e32 v3, 64, v3
	v_add_u32_e32 v234, 12, v0
	v_cndmask_b32_e64 v230, v234, v2, vcc
	v_max_i32_e32 v242, 0, v230
	v_lshl_add_u32 v242, v242, 9, v89
	v_add_u32_e32 v235, 8, v0
	v_add_u32_e32 v239, 4, v2
	v_cndmask_b32_e64 v231, v235, v239, vcc
	v_max_i32_e32 v243, 0, v231
	v_lshl_add_u32 v243, v243, 9, v89
	v_add_u32_e32 v236, 4, v0
	v_add_u32_e32 v240, 8, v2
	v_cndmask_b32_e64 v232, v236, v240, vcc
	v_max_i32_e32 v244, 0, v232
	v_lshl_add_u32 v244, v244, 9, v89
	v_add_u32_e32 v241, 12, v2
	v_cndmask_b32_e64 v233, v0, v241, vcc
	v_max_i32_e32 v245, 0, v233
	v_lshl_add_u32 v245, v245, 9, v89
	v_cmp_lt_i32_e64 s[98:99], -1, v230
	v_cmp_lt_i32_e64 s[100:101], -1, v231
	v_cmp_lt_i32_e64 s[38:39], -1, v232
	v_cndmask_b32_e64 v242, v246, v242, s[98:99]
	v_cmp_lt_i32_e64 s[98:99], -1, v233
	v_cndmask_b32_e64 v243, v246, v243, s[100:101]
	v_cndmask_b32_e64 v244, v246, v244, s[38:39]
	s_nop 0
	v_cndmask_b32_e64 v245, v246, v245, s[98:99]
	s_add_i32 s33, s33, 1
	s_cmp_lt_i32 s33, s19
	s_waitcnt lgkmcnt(0)
	v_mfma_f32_16x16x32_bf16 v[16:19], v[214:217], v[20:23], v[16:19]
	v_mfma_f32_16x16x32_bf16 v[12:15], v[218:221], v[20:23], v[12:15]
	v_mfma_f32_16x16x32_bf16 v[8:11], v[222:225], v[20:23], v[8:11]
	v_mfma_f32_16x16x32_bf16 v[4:7], v[226:229], v[20:23], v[4:7]
	s_cbranch_scc1 .LBB0_721
	s_branch .LBB0_723

.LBB0_723:
	s_add_i32 s0, s41, 16
	s_ashr_i32 s19, s0, 1
	s_max_i32 s26, s19, 0
	s_and_b64 s[0:1], vcc, exec
	s_cselect_b32 s0, 0, s26
	s_add_i32 s1, s41, 28
	s_ashr_i32 s33, s1, 1
	s_min_i32 s1, s33, 15
	s_and_b64 s[26:27], vcc, exec
	s_cselect_b32 s36, s1, 15
	s_cmp_gt_i32 s0, s36
	s_cbranch_scc1 .LBB0_726
	s_lshl_b32 s1, s0, 1
	s_add_i32 s37, s0, -1
	v_or_b32_e32 v0, s1, v101
	s_lshl_b32 s0, s0, 6
	v_sub_u32_e32 v0, v0, v88
	v_subrev_u32_e32 v2, s1, v92
	v_add3_u32 v3, v91, s0, v99
	s_add_i32 s0, 0, 0x9000
	v_mov_b32_e32 v20, 0
	v_subrev_u32_e32 v0, 28, v0
	v_add_u32_e32 v2, 28, v2
	v_add3_u32 v3, v3, v97, s0
	v_mov_b32_e32 v21, v20
	v_mov_b32_e32 v22, v20
	v_mov_b32_e32 v23, v20
	v_mov_b32_e32 v24, v20
	v_mov_b32_e32 v25, v20
	v_mov_b32_e32 v26, v20
	v_mov_b32_e32 v27, v20
	v_mov_b32_e32 v28, v20
	v_mov_b32_e32 v29, v20
	v_mov_b32_e32 v30, v20
	v_mov_b32_e32 v31, v20
	v_mov_b32_e32 v32, v20
	v_mov_b32_e32 v33, v20
	v_mov_b32_e32 v34, v20
	v_mov_b32_e32 v35, v20
	v_add_u32_e32 v234, 12, v0
	v_add_u32_e32 v238, -12, v2
	v_cndmask_b32_e64 v230, v234, v238, vcc
	v_max_i32_e32 v242, 0, v230
	v_lshl_add_u32 v242, v242, 9, v89
	v_add_u32_e32 v235, 8, v0
	v_add_u32_e32 v239, -8, v2
	v_cndmask_b32_e64 v231, v235, v239, vcc
	v_max_i32_e32 v243, 0, v231
	v_lshl_add_u32 v243, v243, 9, v89
	v_add_u32_e32 v236, 4, v0
	v_add_u32_e32 v240, -4, v2
	v_cndmask_b32_e64 v232, v236, v240, vcc
	v_max_i32_e32 v244, 0, v232
	v_lshl_add_u32 v244, v244, 9, v89
	v_cndmask_b32_e64 v233, v0, v2, vcc
	v_max_i32_e32 v245, 0, v233
	v_lshl_add_u32 v245, v245, 9, v89
	v_cmp_lt_i32_e64 s[98:99], -1, v230
	v_cmp_lt_i32_e64 s[100:101], -1, v231
	v_cmp_lt_i32_e64 s[38:39], -1, v232
	v_cndmask_b32_e64 v242, v246, v242, s[98:99]
	v_cmp_lt_i32_e64 s[98:99], -1, v233
	v_cndmask_b32_e64 v243, v246, v243, s[100:101]
	v_cndmask_b32_e64 v244, v246, v244, s[38:39]
	s_nop 0
	v_cndmask_b32_e64 v245, v246, v245, s[98:99]
.LBB0_725:
	ds_read_b128 v[214:217], v242 offset:4096
	ds_read_b128 v[218:221], v243 offset:4096
	ds_read_b128 v[222:225], v244 offset:4096
	ds_read_b128 v[226:229], v245 offset:4096
	ds_read_b128 v[36:39], v3
	v_add_u32_e32 v0, 2, v0
	v_add_u32_e32 v2, -2, v2
	v_add_u32_e32 v3, 64, v3
	v_add_u32_e32 v234, 12, v0
	v_add_u32_e32 v238, -12, v2
	v_cndmask_b32_e64 v230, v234, v238, vcc
	v_max_i32_e32 v242, 0, v230
	v_lshl_add_u32 v242, v242, 9, v89
	v_add_u32_e32 v235, 8, v0
	v_add_u32_e32 v239, -8, v2
	v_cndmask_b32_e64 v231, v235, v239, vcc
	v_max_i32_e32 v243, 0, v231
	v_lshl_add_u32 v243, v243, 9, v89
	v_add_u32_e32 v236, 4, v0
	v_add_u32_e32 v240, -4, v2
	v_cndmask_b32_e64 v232, v236, v240, vcc
	v_max_i32_e32 v244, 0, v232
	v_lshl_add_u32 v244, v244, 9, v89
	v_cndmask_b32_e64 v233, v0, v2, vcc
	v_max_i32_e32 v245, 0, v233
	v_lshl_add_u32 v245, v245, 9, v89
	v_cmp_lt_i32_e64 s[98:99], -1, v230
	v_cmp_lt_i32_e64 s[100:101], -1, v231
	v_cmp_lt_i32_e64 s[38:39], -1, v232
	v_cndmask_b32_e64 v242, v246, v242, s[98:99]
	v_cmp_lt_i32_e64 s[98:99], -1, v233
	v_cndmask_b32_e64 v243, v246, v243, s[100:101]
	v_cndmask_b32_e64 v244, v246, v244, s[38:39]
	s_nop 0
	v_cndmask_b32_e64 v245, v246, v245, s[98:99]
	s_add_i32 s37, s37, 1
	s_cmp_lt_i32 s37, s36
	s_waitcnt lgkmcnt(0)
	v_mfma_f32_16x16x32_bf16 v[32:35], v[214:217], v[36:39], v[32:35]
	v_mfma_f32_16x16x32_bf16 v[28:31], v[218:221], v[36:39], v[28:31]
	v_mfma_f32_16x16x32_bf16 v[24:27], v[222:225], v[36:39], v[24:27]
	v_mfma_f32_16x16x32_bf16 v[20:23], v[226:229], v[36:39], v[20:23]
	s_cbranch_scc1 .LBB0_725
	s_branch .LBB0_727

.LBB0_727:
	s_add_i32 s0, s41, 32
	s_ashr_i32 s36, s0, 1
	s_max_i32 s26, s36, 0
	s_and_b64 s[0:1], vcc, exec
	s_cselect_b32 s0, 0, s26
	s_add_i32 s1, s41, 44
	s_ashr_i32 s37, s1, 1
	s_min_i32 s1, s37, 15
	s_and_b64 s[26:27], vcc, exec
	s_cselect_b32 s40, s1, 15
	s_cmp_gt_i32 s0, s40
	s_cbranch_scc1 .LBB0_730
	s_lshl_b32 s1, s0, 1
	s_add_i32 s42, s0, -1
	v_or_b32_e32 v0, s1, v101
	s_lshl_b32 s0, s0, 6
	v_sub_u32_e32 v0, v0, v88
	v_subrev_u32_e32 v2, s1, v92
	v_add3_u32 v3, v91, s0, v99
	s_add_i32 s0, 0, 0x9000
	v_mov_b32_e32 v36, 0
	v_subrev_u32_e32 v0, 44, v0
	v_add_u32_e32 v2, 44, v2
	v_add3_u32 v3, v3, v97, s0
	v_mov_b32_e32 v37, v36
	v_mov_b32_e32 v38, v36
	v_mov_b32_e32 v39, v36
	v_mov_b32_e32 v40, v36
	v_mov_b32_e32 v41, v36
	v_mov_b32_e32 v42, v36
	v_mov_b32_e32 v43, v36
	v_mov_b32_e32 v44, v36
	v_mov_b32_e32 v45, v36
	v_mov_b32_e32 v46, v36
	v_mov_b32_e32 v47, v36
	v_mov_b32_e32 v48, v36
	v_mov_b32_e32 v49, v36
	v_mov_b32_e32 v50, v36
	v_mov_b32_e32 v51, v36
	v_add_u32_e32 v234, 12, v0
	v_add_u32_e32 v238, -12, v2
	v_cndmask_b32_e64 v230, v234, v238, vcc
	v_max_i32_e32 v242, 0, v230
	v_lshl_add_u32 v242, v242, 9, v89
	v_add_u32_e32 v235, 8, v0
	v_add_u32_e32 v239, -8, v2
	v_cndmask_b32_e64 v231, v235, v239, vcc
	v_max_i32_e32 v243, 0, v231
	v_lshl_add_u32 v243, v243, 9, v89
	v_add_u32_e32 v236, 4, v0
	v_add_u32_e32 v240, -4, v2
	v_cndmask_b32_e64 v232, v236, v240, vcc
	v_max_i32_e32 v244, 0, v232
	v_lshl_add_u32 v244, v244, 9, v89
	v_cndmask_b32_e64 v233, v0, v2, vcc
	v_max_i32_e32 v245, 0, v233
	v_lshl_add_u32 v245, v245, 9, v89
	v_cmp_lt_i32_e64 s[98:99], -1, v230
	v_cmp_lt_i32_e64 s[100:101], -1, v231
	v_cmp_lt_i32_e64 s[38:39], -1, v232
	v_cndmask_b32_e64 v242, v246, v242, s[98:99]
	v_cmp_lt_i32_e64 s[98:99], -1, v233
	v_cndmask_b32_e64 v243, v246, v243, s[100:101]
	v_cndmask_b32_e64 v244, v246, v244, s[38:39]
	s_nop 0
	v_cndmask_b32_e64 v245, v246, v245, s[98:99]
.LBB0_729:
	ds_read_b128 v[214:217], v242 offset:4096
	ds_read_b128 v[218:221], v243 offset:4096
	ds_read_b128 v[222:225], v244 offset:4096
	ds_read_b128 v[226:229], v245 offset:4096
	ds_read_b128 v[68:71], v3
	v_add_u32_e32 v0, 2, v0
	v_add_u32_e32 v2, -2, v2
	v_add_u32_e32 v3, 64, v3
	v_add_u32_e32 v234, 12, v0
	v_add_u32_e32 v238, -12, v2
	v_cndmask_b32_e64 v230, v234, v238, vcc
	v_max_i32_e32 v242, 0, v230
	v_lshl_add_u32 v242, v242, 9, v89
	v_add_u32_e32 v235, 8, v0
	v_add_u32_e32 v239, -8, v2
	v_cndmask_b32_e64 v231, v235, v239, vcc
	v_max_i32_e32 v243, 0, v231
	v_lshl_add_u32 v243, v243, 9, v89
	v_add_u32_e32 v236, 4, v0
	v_add_u32_e32 v240, -4, v2
	v_cndmask_b32_e64 v232, v236, v240, vcc
	v_max_i32_e32 v244, 0, v232
	v_lshl_add_u32 v244, v244, 9, v89
	v_cndmask_b32_e64 v233, v0, v2, vcc
	v_max_i32_e32 v245, 0, v233
	v_lshl_add_u32 v245, v245, 9, v89
	v_cmp_lt_i32_e64 s[98:99], -1, v230
	v_cmp_lt_i32_e64 s[100:101], -1, v231
	v_cmp_lt_i32_e64 s[38:39], -1, v232
	v_cndmask_b32_e64 v242, v246, v242, s[98:99]
	v_cmp_lt_i32_e64 s[98:99], -1, v233
	v_cndmask_b32_e64 v243, v246, v243, s[100:101]
	v_cndmask_b32_e64 v244, v246, v244, s[38:39]
	s_nop 0
	v_cndmask_b32_e64 v245, v246, v245, s[98:99]
	s_add_i32 s42, s42, 1
	s_cmp_lt_i32 s42, s40
	s_waitcnt lgkmcnt(0)
	v_mfma_f32_16x16x32_bf16 v[48:51], v[214:217], v[68:71], v[48:51]
	v_mfma_f32_16x16x32_bf16 v[44:47], v[218:221], v[68:71], v[44:47]
	v_mfma_f32_16x16x32_bf16 v[40:43], v[222:225], v[68:71], v[40:43]
	v_mfma_f32_16x16x32_bf16 v[36:39], v[226:229], v[68:71], v[36:39]
	s_cbranch_scc1 .LBB0_729
	s_branch .LBB0_731

.LBB0_731:
	s_add_i32 s0, s41, 48
	s_ashr_i32 s40, s0, 1
	s_max_i32 s26, s40, 0
	s_and_b64 s[0:1], vcc, exec
	s_cselect_b32 s0, 0, s26
	s_add_i32 s41, s41, 60
	s_ashr_i32 s41, s41, 1
	s_min_i32 s1, s41, 15
	s_and_b64 s[26:27], vcc, exec
	s_cselect_b32 s42, s1, 15
	s_cmp_gt_i32 s0, s42
	s_cbranch_scc1 .LBB0_734
	s_lshl_b32 s1, s0, 1
	s_add_i32 s43, s0, -1
	v_or_b32_e32 v0, s1, v101
	s_lshl_b32 s0, s0, 6
	v_sub_u32_e32 v0, v0, v88
	v_subrev_u32_e32 v2, s1, v92
	v_add3_u32 v3, v91, s0, v99
	s_add_i32 s0, 0, 0x9000
	v_mov_b32_e32 v68, 0
	v_subrev_u32_e32 v0, 60, v0
	v_add_u32_e32 v2, 60, v2
	v_add3_u32 v3, v3, v97, s0
	v_mov_b32_e32 v69, v68
	v_mov_b32_e32 v70, v68
	v_mov_b32_e32 v71, v68
	v_mov_b32_e32 v72, v68
	v_mov_b32_e32 v73, v68
	v_mov_b32_e32 v74, v68
	v_mov_b32_e32 v75, v68
	v_mov_b32_e32 v76, v68
	v_mov_b32_e32 v77, v68
	v_mov_b32_e32 v78, v68
	v_mov_b32_e32 v79, v68
	v_mov_b32_e32 v80, v68
	v_mov_b32_e32 v81, v68
	v_mov_b32_e32 v82, v68
	v_mov_b32_e32 v83, v68
	v_add_u32_e32 v234, 12, v0
	v_add_u32_e32 v238, -12, v2
	v_cndmask_b32_e64 v230, v234, v238, vcc
	v_max_i32_e32 v242, 0, v230
	v_lshl_add_u32 v242, v242, 9, v89
	v_add_u32_e32 v235, 8, v0
	v_add_u32_e32 v239, -8, v2
	v_cndmask_b32_e64 v231, v235, v239, vcc
	v_max_i32_e32 v243, 0, v231
	v_lshl_add_u32 v243, v243, 9, v89
	v_add_u32_e32 v236, 4, v0
	v_add_u32_e32 v240, -4, v2
	v_cndmask_b32_e64 v232, v236, v240, vcc
	v_max_i32_e32 v244, 0, v232
	v_lshl_add_u32 v244, v244, 9, v89
	v_cndmask_b32_e64 v233, v0, v2, vcc
	v_max_i32_e32 v245, 0, v233
	v_lshl_add_u32 v245, v245, 9, v89
	v_cmp_lt_i32_e64 s[98:99], -1, v230
	v_cmp_lt_i32_e64 s[100:101], -1, v231
	v_cmp_lt_i32_e64 s[38:39], -1, v232
	v_cndmask_b32_e64 v242, v246, v242, s[98:99]
	v_cmp_lt_i32_e64 s[98:99], -1, v233
	v_cndmask_b32_e64 v243, v246, v243, s[100:101]
	v_cndmask_b32_e64 v244, v246, v244, s[38:39]
	s_nop 0
	v_cndmask_b32_e64 v245, v246, v245, s[98:99]
.LBB0_733:
	ds_read_b128 v[214:217], v242 offset:4096
	ds_read_b128 v[218:221], v243 offset:4096
	ds_read_b128 v[222:225], v244 offset:4096
	ds_read_b128 v[226:229], v245 offset:4096
	ds_read_b128 v[84:87], v3
	v_add_u32_e32 v0, 2, v0
	v_add_u32_e32 v2, -2, v2
	v_add_u32_e32 v3, 64, v3
	v_add_u32_e32 v234, 12, v0
	v_add_u32_e32 v238, -12, v2
	v_cndmask_b32_e64 v230, v234, v238, vcc
	v_max_i32_e32 v242, 0, v230
	v_lshl_add_u32 v242, v242, 9, v89
	v_add_u32_e32 v235, 8, v0
	v_add_u32_e32 v239, -8, v2
	v_cndmask_b32_e64 v231, v235, v239, vcc
	v_max_i32_e32 v243, 0, v231
	v_lshl_add_u32 v243, v243, 9, v89
	v_add_u32_e32 v236, 4, v0
	v_add_u32_e32 v240, -4, v2
	v_cndmask_b32_e64 v232, v236, v240, vcc
	v_max_i32_e32 v244, 0, v232
	v_lshl_add_u32 v244, v244, 9, v89
	v_cndmask_b32_e64 v233, v0, v2, vcc
	v_max_i32_e32 v245, 0, v233
	v_lshl_add_u32 v245, v245, 9, v89
	v_cmp_lt_i32_e64 s[98:99], -1, v230
	v_cmp_lt_i32_e64 s[100:101], -1, v231
	v_cmp_lt_i32_e64 s[38:39], -1, v232
	v_cndmask_b32_e64 v242, v246, v242, s[98:99]
	v_cmp_lt_i32_e64 s[98:99], -1, v233
	v_cndmask_b32_e64 v243, v246, v243, s[100:101]
	v_cndmask_b32_e64 v244, v246, v244, s[38:39]
	s_nop 0
	v_cndmask_b32_e64 v245, v246, v245, s[98:99]
	s_add_i32 s43, s43, 1
	s_cmp_lt_i32 s43, s42
	s_waitcnt lgkmcnt(0)
	v_mfma_f32_16x16x32_bf16 v[80:83], v[214:217], v[84:87], v[80:83]
	v_mfma_f32_16x16x32_bf16 v[76:79], v[218:221], v[84:87], v[76:79]
	v_mfma_f32_16x16x32_bf16 v[72:75], v[222:225], v[84:87], v[72:75]
	v_mfma_f32_16x16x32_bf16 v[68:71], v[226:229], v[84:87], v[68:71]
	s_cbranch_scc1 .LBB0_733
	s_branch .LBB0_735

.LBB0_735:
	s_max_i32 s2, s2, 16
	s_and_b64 s[0:1], vcc, exec
	s_cselect_b32 s0, 16, s2
	s_min_i32 s1, s3, 31
	s_and_b64 s[2:3], vcc, exec
	s_cselect_b32 s2, s1, 31
	s_cmp_gt_i32 s0, s2
	s_barrier
	s_waitcnt vmcnt(3)
	ds_write_b128 v94, v[52:55] offset:36864
	s_waitcnt vmcnt(2)
	ds_write_b128 v94, v[56:59] offset:41088
	s_waitcnt vmcnt(1)
	ds_write_b128 v94, v[60:63] offset:45312
	s_waitcnt vmcnt(0)
	ds_write_b128 v94, v[64:67] offset:49536
	s_waitcnt lgkmcnt(0)
	s_barrier
	s_cbranch_scc1 .LBB0_738
	s_lshl_b32 s1, s0, 1
	s_add_i32 s3, s0, -1
	v_or_b32_e32 v0, s1, v101
	s_lshl_b32 s0, s0, 6
	v_sub_u32_e32 v0, v0, v88
	v_add3_u32 v3, v91, s0, v99
	v_readlane_b32 s0, v253, 42
	v_add_u32_e32 v0, -12, v0
	v_subrev_u32_e32 v2, s1, v92
	v_add3_u32 v3, v3, v97, s0
	v_add_u32_e32 v234, 12, v0
	v_cndmask_b32_e64 v230, v234, v2, vcc
	v_max_i32_e32 v242, 0, v230
	v_lshl_add_u32 v242, v242, 9, v89
	v_add_u32_e32 v235, 8, v0
	v_add_u32_e32 v239, 4, v2
	v_cndmask_b32_e64 v231, v235, v239, vcc
	v_max_i32_e32 v243, 0, v231
	v_lshl_add_u32 v243, v243, 9, v89
	v_add_u32_e32 v236, 4, v0
	v_add_u32_e32 v240, 8, v2
	v_cndmask_b32_e64 v232, v236, v240, vcc
	v_max_i32_e32 v244, 0, v232
	v_lshl_add_u32 v244, v244, 9, v89
	v_add_u32_e32 v241, 12, v2
	v_cndmask_b32_e64 v233, v0, v241, vcc
	v_max_i32_e32 v245, 0, v233
	v_lshl_add_u32 v245, v245, 9, v89
	v_cmp_lt_i32_e64 s[98:99], -1, v230
	v_cmp_lt_i32_e64 s[100:101], -1, v231
	v_cmp_lt_i32_e64 s[38:39], -1, v232
	v_cndmask_b32_e64 v242, v246, v242, s[98:99]
	v_cmp_lt_i32_e64 s[98:99], -1, v233
	v_cndmask_b32_e64 v243, v246, v243, s[100:101]
	v_cndmask_b32_e64 v244, v246, v244, s[38:39]
	s_nop 0
	v_cndmask_b32_e64 v245, v246, v245, s[98:99]
.LBB0_737:
	ds_read_b128 v[214:217], v242 offset:4096
	ds_read_b128 v[218:221], v243 offset:4096
	ds_read_b128 v[222:225], v244 offset:4096
	ds_read_b128 v[226:229], v245 offset:4096
	ds_read_b128 v[52:55], v3
	v_add_u32_e32 v0, 2, v0
	v_add_u32_e32 v2, -2, v2
	v_add_u32_e32 v3, 64, v3
	v_add_u32_e32 v234, 12, v0
	v_cndmask_b32_e64 v230, v234, v2, vcc
	v_max_i32_e32 v242, 0, v230
	v_lshl_add_u32 v242, v242, 9, v89
	v_add_u32_e32 v235, 8, v0
	v_add_u32_e32 v239, 4, v2
	v_cndmask_b32_e64 v231, v235, v239, vcc
	v_max_i32_e32 v243, 0, v231
	v_lshl_add_u32 v243, v243, 9, v89
	v_add_u32_e32 v236, 4, v0
	v_add_u32_e32 v240, 8, v2
	v_cndmask_b32_e64 v232, v236, v240, vcc
	v_max_i32_e32 v244, 0, v232
	v_lshl_add_u32 v244, v244, 9, v89
	v_add_u32_e32 v241, 12, v2
	v_cndmask_b32_e64 v233, v0, v241, vcc
	v_max_i32_e32 v245, 0, v233
	v_lshl_add_u32 v245, v245, 9, v89
	v_cmp_lt_i32_e64 s[98:99], -1, v230
	v_cmp_lt_i32_e64 s[100:101], -1, v231
	v_cmp_lt_i32_e64 s[38:39], -1, v232
	v_cndmask_b32_e64 v242, v246, v242, s[98:99]
	v_cmp_lt_i32_e64 s[98:99], -1, v233
	v_cndmask_b32_e64 v243, v246, v243, s[100:101]
	v_cndmask_b32_e64 v244, v246, v244, s[38:39]
	s_nop 0
	v_cndmask_b32_e64 v245, v246, v245, s[98:99]
	s_add_i32 s3, s3, 1
	s_cmp_lt_i32 s3, s2
	s_waitcnt lgkmcnt(0)
	v_mfma_f32_16x16x32_bf16 v[16:19], v[214:217], v[52:55], v[16:19]
	v_mfma_f32_16x16x32_bf16 v[12:15], v[218:221], v[52:55], v[12:15]
	v_mfma_f32_16x16x32_bf16 v[8:11], v[222:225], v[52:55], v[8:11]
	v_mfma_f32_16x16x32_bf16 v[4:7], v[226:229], v[52:55], v[4:7]
	s_cbranch_scc1 .LBB0_737
.LBB0_738:
	s_max_i32 s2, s19, 16
	s_and_b64 s[0:1], vcc, exec
	s_cselect_b32 s0, 16, s2
	s_min_i32 s1, s33, 31
	s_and_b64 s[2:3], vcc, exec
	s_cselect_b32 s2, s1, 31
	s_cmp_gt_i32 s0, s2
	s_cbranch_scc1 .LBB0_741
	s_lshl_b32 s1, s0, 1
	s_add_i32 s3, s0, -1
	v_or_b32_e32 v0, s1, v101
	s_lshl_b32 s0, s0, 6
	v_sub_u32_e32 v0, v0, v88
	v_subrev_u32_e32 v2, s1, v92
	v_add3_u32 v3, v91, s0, v99
	v_readlane_b32 s0, v253, 42
	v_subrev_u32_e32 v0, 28, v0
	v_add_u32_e32 v2, 28, v2
	v_add3_u32 v3, v3, v97, s0
	v_add_u32_e32 v234, 12, v0
	v_add_u32_e32 v238, -12, v2
	v_cndmask_b32_e64 v230, v234, v238, vcc
	v_max_i32_e32 v242, 0, v230
	v_lshl_add_u32 v242, v242, 9, v89
	v_add_u32_e32 v235, 8, v0
	v_add_u32_e32 v239, -8, v2
	v_cndmask_b32_e64 v231, v235, v239, vcc
	v_max_i32_e32 v243, 0, v231
	v_lshl_add_u32 v243, v243, 9, v89
	v_add_u32_e32 v236, 4, v0
	v_add_u32_e32 v240, -4, v2
	v_cndmask_b32_e64 v232, v236, v240, vcc
	v_max_i32_e32 v244, 0, v232
	v_lshl_add_u32 v244, v244, 9, v89
	v_cndmask_b32_e64 v233, v0, v2, vcc
	v_max_i32_e32 v245, 0, v233
	v_lshl_add_u32 v245, v245, 9, v89
	v_cmp_lt_i32_e64 s[98:99], -1, v230
	v_cmp_lt_i32_e64 s[100:101], -1, v231
	v_cmp_lt_i32_e64 s[38:39], -1, v232
	v_cndmask_b32_e64 v242, v246, v242, s[98:99]
	v_cmp_lt_i32_e64 s[98:99], -1, v233
	v_cndmask_b32_e64 v243, v246, v243, s[100:101]
	v_cndmask_b32_e64 v244, v246, v244, s[38:39]
	s_nop 0
	v_cndmask_b32_e64 v245, v246, v245, s[98:99]
.LBB0_740:
	ds_read_b128 v[214:217], v242 offset:4096
	ds_read_b128 v[218:221], v243 offset:4096
	ds_read_b128 v[222:225], v244 offset:4096
	ds_read_b128 v[226:229], v245 offset:4096
	ds_read_b128 v[52:55], v3
	v_add_u32_e32 v0, 2, v0
	v_add_u32_e32 v2, -2, v2
	v_add_u32_e32 v3, 64, v3
	v_add_u32_e32 v234, 12, v0
	v_add_u32_e32 v238, -12, v2
	v_cndmask_b32_e64 v230, v234, v238, vcc
	v_max_i32_e32 v242, 0, v230
	v_lshl_add_u32 v242, v242, 9, v89
	v_add_u32_e32 v235, 8, v0
	v_add_u32_e32 v239, -8, v2
	v_cndmask_b32_e64 v231, v235, v239, vcc
	v_max_i32_e32 v243, 0, v231
	v_lshl_add_u32 v243, v243, 9, v89
	v_add_u32_e32 v236, 4, v0
	v_add_u32_e32 v240, -4, v2
	v_cndmask_b32_e64 v232, v236, v240, vcc
	v_max_i32_e32 v244, 0, v232
	v_lshl_add_u32 v244, v244, 9, v89
	v_cndmask_b32_e64 v233, v0, v2, vcc
	v_max_i32_e32 v245, 0, v233
	v_lshl_add_u32 v245, v245, 9, v89
	v_cmp_lt_i32_e64 s[98:99], -1, v230
	v_cmp_lt_i32_e64 s[100:101], -1, v231
	v_cmp_lt_i32_e64 s[38:39], -1, v232
	v_cndmask_b32_e64 v242, v246, v242, s[98:99]
	v_cmp_lt_i32_e64 s[98:99], -1, v233
	v_cndmask_b32_e64 v243, v246, v243, s[100:101]
	v_cndmask_b32_e64 v244, v246, v244, s[38:39]
	s_nop 0
	v_cndmask_b32_e64 v245, v246, v245, s[98:99]
	s_add_i32 s3, s3, 1
	s_cmp_lt_i32 s3, s2
	s_waitcnt lgkmcnt(0)
	v_mfma_f32_16x16x32_bf16 v[32:35], v[214:217], v[52:55], v[32:35]
	v_mfma_f32_16x16x32_bf16 v[28:31], v[218:221], v[52:55], v[28:31]
	v_mfma_f32_16x16x32_bf16 v[24:27], v[222:225], v[52:55], v[24:27]
	v_mfma_f32_16x16x32_bf16 v[20:23], v[226:229], v[52:55], v[20:23]
	s_cbranch_scc1 .LBB0_740
.LBB0_741:
	s_max_i32 s2, s36, 16
	s_and_b64 s[0:1], vcc, exec
	s_cselect_b32 s0, 16, s2
	s_min_i32 s1, s37, 31
	s_and_b64 s[2:3], vcc, exec
	s_cselect_b32 s2, s1, 31
	s_cmp_gt_i32 s0, s2
	s_cbranch_scc1 .LBB0_744
	s_lshl_b32 s1, s0, 1
	s_add_i32 s3, s0, -1
	v_or_b32_e32 v0, s1, v101
	s_lshl_b32 s0, s0, 6
	v_sub_u32_e32 v0, v0, v88
	v_subrev_u32_e32 v2, s1, v92
	v_add3_u32 v3, v91, s0, v99
	v_readlane_b32 s0, v253, 42
	v_subrev_u32_e32 v0, 44, v0
	v_add_u32_e32 v2, 44, v2
	v_add3_u32 v3, v3, v97, s0
	v_add_u32_e32 v234, 12, v0
	v_add_u32_e32 v238, -12, v2
	v_cndmask_b32_e64 v230, v234, v238, vcc
	v_max_i32_e32 v242, 0, v230
	v_lshl_add_u32 v242, v242, 9, v89
	v_add_u32_e32 v235, 8, v0
	v_add_u32_e32 v239, -8, v2
	v_cndmask_b32_e64 v231, v235, v239, vcc
	v_max_i32_e32 v243, 0, v231
	v_lshl_add_u32 v243, v243, 9, v89
	v_add_u32_e32 v236, 4, v0
	v_add_u32_e32 v240, -4, v2
	v_cndmask_b32_e64 v232, v236, v240, vcc
	v_max_i32_e32 v244, 0, v232
	v_lshl_add_u32 v244, v244, 9, v89
	v_cndmask_b32_e64 v233, v0, v2, vcc
	v_max_i32_e32 v245, 0, v233
	v_lshl_add_u32 v245, v245, 9, v89
	v_cmp_lt_i32_e64 s[98:99], -1, v230
	v_cmp_lt_i32_e64 s[100:101], -1, v231
	v_cmp_lt_i32_e64 s[38:39], -1, v232
	v_cndmask_b32_e64 v242, v246, v242, s[98:99]
	v_cmp_lt_i32_e64 s[98:99], -1, v233
	v_cndmask_b32_e64 v243, v246, v243, s[100:101]
	v_cndmask_b32_e64 v244, v246, v244, s[38:39]
	s_nop 0
	v_cndmask_b32_e64 v245, v246, v245, s[98:99]
.LBB0_743:
	ds_read_b128 v[214:217], v242 offset:4096
	ds_read_b128 v[218:221], v243 offset:4096
	ds_read_b128 v[222:225], v244 offset:4096
	ds_read_b128 v[226:229], v245 offset:4096
	ds_read_b128 v[52:55], v3
	v_add_u32_e32 v0, 2, v0
	v_add_u32_e32 v2, -2, v2
	v_add_u32_e32 v3, 64, v3
	v_add_u32_e32 v234, 12, v0
	v_add_u32_e32 v238, -12, v2
	v_cndmask_b32_e64 v230, v234, v238, vcc
	v_max_i32_e32 v242, 0, v230
	v_lshl_add_u32 v242, v242, 9, v89
	v_add_u32_e32 v235, 8, v0
	v_add_u32_e32 v239, -8, v2
	v_cndmask_b32_e64 v231, v235, v239, vcc
	v_max_i32_e32 v243, 0, v231
	v_lshl_add_u32 v243, v243, 9, v89
	v_add_u32_e32 v236, 4, v0
	v_add_u32_e32 v240, -4, v2
	v_cndmask_b32_e64 v232, v236, v240, vcc
	v_max_i32_e32 v244, 0, v232
	v_lshl_add_u32 v244, v244, 9, v89
	v_cndmask_b32_e64 v233, v0, v2, vcc
	v_max_i32_e32 v245, 0, v233
	v_lshl_add_u32 v245, v245, 9, v89
	v_cmp_lt_i32_e64 s[98:99], -1, v230
	v_cmp_lt_i32_e64 s[100:101], -1, v231
	v_cmp_lt_i32_e64 s[38:39], -1, v232
	v_cndmask_b32_e64 v242, v246, v242, s[98:99]
	v_cmp_lt_i32_e64 s[98:99], -1, v233
	v_cndmask_b32_e64 v243, v246, v243, s[100:101]
	v_cndmask_b32_e64 v244, v246, v244, s[38:39]
	s_nop 0
	v_cndmask_b32_e64 v245, v246, v245, s[98:99]
	s_add_i32 s3, s3, 1
	s_cmp_lt_i32 s3, s2
	s_waitcnt lgkmcnt(0)
	v_mfma_f32_16x16x32_bf16 v[48:51], v[214:217], v[52:55], v[48:51]
	v_mfma_f32_16x16x32_bf16 v[44:47], v[218:221], v[52:55], v[44:47]
	v_mfma_f32_16x16x32_bf16 v[40:43], v[222:225], v[52:55], v[40:43]
	v_mfma_f32_16x16x32_bf16 v[36:39], v[226:229], v[52:55], v[36:39]
	s_cbranch_scc1 .LBB0_743
.LBB0_744:
	s_max_i32 s2, s40, 16
	s_and_b64 s[0:1], vcc, exec
	s_cselect_b32 s0, 16, s2
	s_min_i32 s1, s41, 31
	s_and_b64 s[2:3], vcc, exec
	s_cselect_b32 s2, s1, 31
	s_mov_b64 s[38:39], -1
	s_cmp_le_i32 s0, s2
	v_add_u32_e32 v0, 48, v88
	v_add_u32_e32 v2, 52, v88
	v_add_u32_e32 v3, 56, v88
	v_add_u32_e32 v102, 60, v88
	s_cbranch_scc0 .LBB0_748
	s_lshl_b32 s1, s0, 1
	v_or_b32_e32 v52, s1, v101
	v_add_u32_e32 v92, 60, v88
	v_sub_u32_e32 v52, v52, v88
	s_add_i32 s3, s0, -1
	v_subrev_u32_e32 v103, 60, v52
	v_sub_u32_e32 v52, v92, v101
	s_lshl_b32 s0, s0, 6
	v_subrev_u32_e32 v101, s1, v52
	v_add3_u32 v52, v91, s0, v99
	v_readlane_b32 s0, v253, 42
	v_mov_b64_e32 v[56:57], v[72:73]
	v_mov_b64_e32 v[60:61], v[76:77]
	v_add3_u32 v91, v52, v97, s0
	v_mov_b64_e32 v[52:53], v[68:69]
	v_mov_b64_e32 v[64:65], v[80:81]
	v_add_u32_e32 v98, 48, v88
	v_add_u32_e32 v96, 52, v88
	v_add_u32_e32 v94, 56, v88
	v_mov_b64_e32 v[54:55], v[70:71]
	v_mov_b64_e32 v[58:59], v[74:75]
	v_mov_b64_e32 v[62:63], v[78:79]
	v_mov_b64_e32 v[66:67], v[82:83]
	v_add_u32_e32 v234, 12, v103
	v_add_u32_e32 v238, -12, v101
	v_cndmask_b32_e64 v230, v234, v238, vcc
	v_max_i32_e32 v242, 0, v230
	v_lshl_add_u32 v242, v242, 9, v89
	v_add_u32_e32 v235, 8, v103
	v_add_u32_e32 v239, -8, v101
	v_cndmask_b32_e64 v231, v235, v239, vcc
	v_max_i32_e32 v243, 0, v231
	v_lshl_add_u32 v243, v243, 9, v89
	v_add_u32_e32 v236, 4, v103
	v_add_u32_e32 v240, -4, v101
	v_cndmask_b32_e64 v232, v236, v240, vcc
	v_max_i32_e32 v244, 0, v232
	v_lshl_add_u32 v244, v244, 9, v89
	v_cndmask_b32_e64 v233, v103, v101, vcc
	v_max_i32_e32 v245, 0, v233
	v_lshl_add_u32 v245, v245, 9, v89
	v_cmp_lt_i32_e64 s[98:99], -1, v230
	v_cmp_lt_i32_e64 s[100:101], -1, v231
	v_cmp_lt_i32_e64 s[38:39], -1, v232
	v_cndmask_b32_e64 v242, v246, v242, s[98:99]
	v_cmp_lt_i32_e64 s[98:99], -1, v233
	v_cndmask_b32_e64 v243, v246, v243, s[100:101]
	v_cndmask_b32_e64 v244, v246, v244, s[38:39]
	s_nop 0
	v_cndmask_b32_e64 v245, v246, v245, s[98:99]
.LBB0_746:
	ds_read_b128 v[214:217], v242 offset:4096
	ds_read_b128 v[218:221], v243 offset:4096
	ds_read_b128 v[222:225], v244 offset:4096
	ds_read_b128 v[226:229], v245 offset:4096
	ds_read_b128 v[84:87], v91
	v_add_u32_e32 v103, 2, v103
	v_add_u32_e32 v101, -2, v101
	v_add_u32_e32 v91, 64, v91
	v_add_u32_e32 v234, 12, v103
	v_add_u32_e32 v238, -12, v101
	v_cndmask_b32_e64 v230, v234, v238, vcc
	v_max_i32_e32 v242, 0, v230
	v_lshl_add_u32 v242, v242, 9, v89
	v_add_u32_e32 v235, 8, v103
	v_add_u32_e32 v239, -8, v101
	v_cndmask_b32_e64 v231, v235, v239, vcc
	v_max_i32_e32 v243, 0, v231
	v_lshl_add_u32 v243, v243, 9, v89
	v_add_u32_e32 v236, 4, v103
	v_add_u32_e32 v240, -4, v101
	v_cndmask_b32_e64 v232, v236, v240, vcc
	v_max_i32_e32 v244, 0, v232
	v_lshl_add_u32 v244, v244, 9, v89
	v_cndmask_b32_e64 v233, v103, v101, vcc
	v_max_i32_e32 v245, 0, v233
	v_lshl_add_u32 v245, v245, 9, v89
	v_cmp_lt_i32_e64 s[98:99], -1, v230
	v_cmp_lt_i32_e64 s[100:101], -1, v231
	v_cmp_lt_i32_e64 s[38:39], -1, v232
	v_cndmask_b32_e64 v242, v246, v242, s[98:99]
	v_cmp_lt_i32_e64 s[98:99], -1, v233
	v_cndmask_b32_e64 v243, v246, v243, s[100:101]
	v_cndmask_b32_e64 v244, v246, v244, s[38:39]
	s_nop 0
	v_cndmask_b32_e64 v245, v246, v245, s[98:99]
	s_add_i32 s3, s3, 1
	s_cmp_lt_i32 s3, s2
	s_waitcnt lgkmcnt(0)
	v_mfma_f32_16x16x32_bf16 v[64:67], v[214:217], v[84:87], v[64:67]
	v_mfma_f32_16x16x32_bf16 v[60:63], v[218:221], v[84:87], v[60:63]
	v_mfma_f32_16x16x32_bf16 v[56:59], v[222:225], v[84:87], v[56:59]
	v_mfma_f32_16x16x32_bf16 v[52:55], v[226:229], v[84:87], v[52:55]
	s_cbranch_scc1 .LBB0_746
	s_mov_b64 s[38:39], 0
